# v34 + 256-byte alignment of the two FFN-up conv-epilogue loop heads (extended placement pinning)
# speedup vs baseline: 1.0022x; 1.0022x over previous
.LBB0_386:
	v_readfirstlane_b32 s21, v191
	s_mov_b32 s20, 0
	.p2align 8

.LBB0_410:
	v_readfirstlane_b32 s21, v44
	s_mov_b32 s20, 0
	.p2align 8
